# S5-out row-sum reduction via permlane16/32 swap instead of two ds_bpermute hops (bit-identical), on top of DPP LayerNorm reductions
# baseline (speedup 1.0000x reference)
; #define LAS __attribute__((address_space(3)))
; #define GAS __attribute__((address_space(1)))
; #define LDS_WAIT() asm volatile("s_waitcnt lgkmcnt(0)" ::: "memory")
; template <bool PB>
; __device__ __forceinline__ void phase_s5(const PView& p, int l, LAS unsigned char* lds, int lane, int wave) {
;     ...
;             const bf16x8 ufC = *(const GAS bf16x8*)(up + (size_t)scn * 16 * DIN);
;             const bf16x8 uf = (q < 2) ? ufA : zero8;
; #pragma unroll
;             for (int i = 0; i < 8; ++i) { const f32x4 d = __builtin_amdgcn_mfma_f32_16x16x32_bf16(bbf[i], uf, zero4, 0, 0, 0);
;                 u32x2 w; w.x = cvt_pk_bf16(d[0], d[1]); w.y = cvt_pk_bf16(d[2], d[3]); *(LAS u32x2*)(BuL + c * 68 + 8 * i + 2 * q) = w; }
;             LDS_WAIT();
;             unsigned bu[16];
; #pragma unroll
;             for (int s = 0; s < 16; ++s) bu[s] = BuL[s * 68 + lane];
; #pragma unroll
;             for (int s = 0; s < 16; ++s) { const float bx = bf2f((unsigned short)(bu[s] & 0xffff)), by = __builtin_bit_cast(float, bu[s] & 0xffff0000u);
;                 const float nr = fmaf(ar, hr, fmaf(-ai, hi, bx)), ni = fmaf(ar, hi, fmaf(ai, hr, by)); hr = nr; hi = ni;
;                 if (PB) HL[s * 68 + lane] = cvt_pk_bf16(hr, hi); }
;             LDS_WAIT();
;             if (PB) {
;                 f32x4 y = zero4;
; #pragma unroll
;                 for (int kk = 0; kk < 4; ++kk) { const bf16x8 hf = *(const LAS bf16x8*)((const LAS bf16_t*)HL + c * 136 + 32 * kk + 8 * q); y = __builtin_amdgcn_mfma_f32_16x16x32_bf16(cfr[kk], hf, y, 0, 0, 0); }
;                 y = __builtin_amdgcn_mfma_f32_16x16x32_bf16(dfr, uf, y, 0, 0, 0);
;                 bf16x8 gf = zero8;
;                 { const unsigned w0 = cvt_pk_bf16(gelu_tanh(y[0]), gelu_tanh(y[1])), w1 = cvt_pk_bf16(gelu_tanh(y[2]), gelu_tanh(y[3]));
;                   gf[0] = (short)(w0 & 0xffff); gf[1] = (short)(w0 >> 16); gf[2] = (short)(w1 & 0xffff); gf[3] = (short)(w1 >> 16); }
;                 const f32x4 z0 = __builtin_amdgcn_mfma_f32_16x16x32_bf16(glf[0], gf, zero4, 0, 0, 0);
;                 const f32x4 z1 = __builtin_amdgcn_mfma_f32_16x16x32_bf16(glf[1], gf, zero4, 0, 0, 0);
;                 float o[4]; float ss = 0.f;
; #pragma unroll
;                 for (int r = 0; r < 4; ++r) { o[r] = (z0[r] + gb0[r]) * sigmoidf_(z1[r] + gb1[r]); ss += o[r] * o[r]; }
.LBB0_334:
	s_min_u32 s10, s26, 29
	v_cndmask_b32_e64 v83, 0, v83, s[0:1]
	v_cndmask_b32_e64 v82, 0, v82, s[0:1]
	v_cndmask_b32_e64 v81, 0, v81, s[0:1]
	v_cndmask_b32_e64 v80, 0, v80, s[0:1]
	s_mul_i32 s98, s10, 0x18000
	s_waitcnt lgkmcnt(0)
	ds_read_b128 v[176:179], v162 offset:4352
	ds_read_b128 v[180:183], v162 offset:4416
	ds_read_b128 v[184:187], v162 offset:4480
	ds_read_b128 v[188:191], v162 offset:4544
	v_lshl_add_u64 v[0:1], v[110:111], 0, s[98:99]
	v_mfma_f32_16x16x32_bf16 v[120:123], v[8:11], v[80:83], 0
	v_add_co_u32_e32 v0, vcc, 0x30000, v0
	v_add_u32_e32 v3, v99, v86
	v_mfma_f32_16x16x32_bf16 v[124:127], v[4:7], v[80:83], 0
	v_addc_co_u32_e32 v1, vcc, 0, v1, vcc
	global_load_dwordx4 v[76:79], v[0:1], off
	s_nop 2
	v_cvt_pk_bf16_f32 v0, v120, v121
	v_cvt_pk_bf16_f32 v1, v122, v123
	v_mfma_f32_16x16x32_bf16 v[120:123], v[16:19], v[80:83], 0
	v_cvt_pk_bf16_f32 v124, v124, v125
	v_cvt_pk_bf16_f32 v125, v126, v127
	ds_write2_b64 v3, v[0:1], v[124:125] offset1:4
	v_mfma_f32_16x16x32_bf16 v[124:127], v[12:15], v[80:83], 0
	v_add_u32_e32 v117, 0x1000, v160
	s_nop 2
	v_cvt_pk_bf16_f32 v0, v120, v121
	v_cvt_pk_bf16_f32 v1, v122, v123
	v_mfma_f32_16x16x32_bf16 v[120:123], v[24:27], v[80:83], 0
	s_nop 0
	v_cvt_pk_bf16_f32 v124, v124, v125
	v_cvt_pk_bf16_f32 v125, v126, v127
	ds_write2_b64 v3, v[0:1], v[124:125] offset0:8 offset1:12
	v_mfma_f32_16x16x32_bf16 v[124:127], v[20:23], v[80:83], 0
	s_nop 2
	v_cvt_pk_bf16_f32 v0, v120, v121
	v_cvt_pk_bf16_f32 v1, v122, v123
	v_mfma_f32_16x16x32_bf16 v[120:123], v[32:35], v[80:83], 0
	s_nop 1
	v_cvt_pk_bf16_f32 v124, v124, v125
	v_cvt_pk_bf16_f32 v125, v126, v127
	ds_write2_b64 v3, v[0:1], v[124:125] offset0:16 offset1:20
	s_nop 2
	v_cvt_pk_bf16_f32 v0, v120, v121
	v_cvt_pk_bf16_f32 v1, v122, v123
	v_mfma_f32_16x16x32_bf16 v[120:123], v[28:31], v[80:83], 0
	s_nop 7
	v_cvt_pk_bf16_f32 v120, v120, v121
	v_cvt_pk_bf16_f32 v121, v122, v123
	ds_write2_b64 v3, v[0:1], v[120:121] offset0:24 offset1:28
	s_waitcnt lgkmcnt(0)
	ds_read2_b32 v[0:1], v133 offset1:68
	ds_read2_b32 v[120:121], v133 offset0:136 offset1:204
	v_add_u32_e32 v3, 0x400, v133
	ds_read2_b32 v[122:123], v3 offset0:16 offset1:84
	ds_read2_b32 v[124:125], v3 offset0:152 offset1:220
	v_add_u32_e32 v3, 0x800, v133
	s_waitcnt lgkmcnt(3)
	v_lshlrev_b32_e32 v138, 16, v0
	v_and_b32_e32 v139, 0xffff0000, v0
	v_mfma_f32_16x16x32_bf16 v[172:175], v[36:39], v[176:179], 0
	v_pk_fma_f32 v[138:139], v[104:105], v[118:119], v[138:139]
	v_mfma_f32_16x16x32_bf16 v[172:175], v[40:43], v[180:183], v[172:175]
	v_lshlrev_b32_e32 v0, 16, v1
	v_pk_fma_f32 v[118:119], v[112:113], v[118:119], v[138:139] op_sel:[0,1,0] op_sel_hi:[1,0,1]
	v_mfma_f32_16x16x32_bf16 v[172:175], v[44:47], v[184:187], v[172:175]
	v_and_b32_e32 v1, 0xffff0000, v1
	v_mfma_f32_16x16x32_bf16 v[172:175], v[48:51], v[188:191], v[172:175]
	ds_read2_b32 v[126:127], v3 offset0:32 offset1:100
	ds_read2_b32 v[128:129], v3 offset0:168 offset1:236
	v_mfma_f32_16x16x32_bf16 v[192:195], v[72:75], v[168:171], v[172:175]
	v_add_u32_e32 v3, 0xc00, v133
	v_pk_fma_f32 v[0:1], v[104:105], v[118:119], v[0:1] op_sel:[0,1,0] op_sel_hi:[1,0,1]
	ds_read2_b32 v[130:131], v3 offset0:48 offset1:116
	ds_read2_b32 v[136:137], v3 offset0:184 offset1:252
	v_cvt_pk_bf16_f32 v3, v118, v119
	v_pk_fma_f32 v[0:1], v[112:113], v[118:119], v[0:1]
	s_waitcnt lgkmcnt(6)
	v_lshlrev_b32_e32 v118, 16, v120
	v_mul_f32_e32 v198, 0x3d372713, v194
	v_mul_f32_e32 v196, 0x3d372713, v192
	v_mul_f32_e32 v197, 0x3d372713, v193
	v_fma_f32 v198, v194, v198, 1.0
	v_mul_f32_e32 v199, 0x3d372713, v195
	v_and_b32_e32 v119, 0xffff0000, v120
	v_fma_f32 v196, v192, v196, 1.0
	v_pk_fma_f32 v[118:119], v[104:105], v[0:1], v[118:119] op_sel:[0,1,0] op_sel_hi:[1,0,1]
	v_fma_f32 v197, v193, v197, 1.0
	v_cvt_pk_bf16_f32 v103, v0, v1
	v_pk_fma_f32 v[0:1], v[112:113], v[0:1], v[118:119]
	v_mul_f32_e32 v198, v194, v198
	v_lshlrev_b32_e32 v118, 16, v121
	v_fma_f32 v199, v195, v199, 1.0
	v_and_b32_e32 v119, 0xffff0000, v121
	v_mul_f32_e32 v196, v192, v196
	v_pk_fma_f32 v[118:119], v[104:105], v[0:1], v[118:119] op_sel:[0,1,0] op_sel_hi:[1,0,1]
	ds_write2_b32 v117, v3, v103 offset0:64 offset1:132
	v_mul_f32_e32 v197, v193, v197
	v_cvt_pk_bf16_f32 v3, v0, v1
	v_mul_f32_e32 v198, 0xc0135761, v198
	v_pk_fma_f32 v[0:1], v[112:113], v[0:1], v[118:119]
	s_waitcnt lgkmcnt(6)
	v_mul_f32_e32 v199, v195, v199
	v_lshlrev_b32_e32 v118, 16, v122
	v_mul_f32_e32 v196, 0xc0135761, v196
	v_and_b32_e32 v119, 0xffff0000, v122
	v_pk_fma_f32 v[118:119], v[104:105], v[0:1], v[118:119] op_sel:[0,1,0] op_sel_hi:[1,0,1]
	v_mul_f32_e32 v197, 0xc0135761, v197
	v_cvt_pk_bf16_f32 v103, v0, v1
	v_exp_f32_e32 v198, v198
	v_pk_fma_f32 v[0:1], v[112:113], v[0:1], v[118:119]
	v_lshlrev_b32_e32 v119, 16, v123
	v_mul_f32_e32 v199, 0xc0135761, v199
	v_and_b32_e32 v118, 0xffff0000, v123
	v_exp_f32_e32 v196, v196
	v_add_u32_e32 v117, 0x1200, v160
	v_pk_fma_f32 v[118:119], v[106:107], v[0:1], v[118:119]
	v_exp_f32_e32 v197, v197
	ds_write2_b32 v117, v3, v103 offset0:72 offset1:140
	v_exp_f32_e32 v199, v199
	v_cvt_pk_bf16_f32 v3, v0, v1
	v_pk_fma_f32 v[0:1], v[112:113], v[0:1], v[118:119] op_sel:[0,1,0] op_sel_hi:[1,0,1]
	v_add_f32_e32 v198, 1.0, v198
	s_waitcnt lgkmcnt(6)
; #define LAS __attribute__((address_space(3)))
; #define GAS __attribute__((address_space(1)))
; __device__ __forceinline__ unsigned cvt_pk_bf16(float lo, float hi) { const f32x2 v = {lo, hi}; const bf16x2_t b = __builtin_convertvector(v, bf16x2_t); return __builtin_bit_cast(unsigned, b); }
; __device__ __forceinline__ float sigmoidf_(float x) { return __builtin_amdgcn_rcpf(1.0f + __builtin_amdgcn_exp2f(-1.44269504f * x)); }
; #define LDS_WAIT() asm volatile("s_waitcnt lgkmcnt(0)" ::: "memory")
; template <bool PB>
; __device__ __forceinline__ void phase_s5(const PView& p, int l, LAS unsigned char* lds, int lane, int wave) {
;     ...
;             for (int s = 0; s < 16; ++s) { const float bx = bf2f((unsigned short)(bu[s] & 0xffff)), by = __builtin_bit_cast(float, bu[s] & 0xffff0000u);
;                 const float nr = fmaf(ar, hr, fmaf(-ai, hi, bx)), ni = fmaf(ar, hi, fmaf(ai, hr, by)); hr = nr; hi = ni;
;                 if (PB) HL[s * 68 + lane] = cvt_pk_bf16(hr, hi); }
;             LDS_WAIT();
;             if (PB) {
;                 f32x4 y = zero4;
; #pragma unroll
;                 for (int kk = 0; kk < 4; ++kk) { const bf16x8 hf = *(const LAS bf16x8*)((const LAS bf16_t*)HL + c * 136 + 32 * kk + 8 * q); y = __builtin_amdgcn_mfma_f32_16x16x32_bf16(cfr[kk], hf, y, 0, 0, 0); }
;                 y = __builtin_amdgcn_mfma_f32_16x16x32_bf16(dfr, uf, y, 0, 0, 0);
;                 bf16x8 gf = zero8;
;                 { const unsigned w0 = cvt_pk_bf16(gelu_tanh(y[0]), gelu_tanh(y[1])), w1 = cvt_pk_bf16(gelu_tanh(y[2]), gelu_tanh(y[3]));
;                   gf[0] = (short)(w0 & 0xffff); gf[1] = (short)(w0 >> 16); gf[2] = (short)(w1 & 0xffff); gf[3] = (short)(w1 >> 16); }
;                 const f32x4 z0 = __builtin_amdgcn_mfma_f32_16x16x32_bf16(glf[0], gf, zero4, 0, 0, 0);
;                 const f32x4 z1 = __builtin_amdgcn_mfma_f32_16x16x32_bf16(glf[1], gf, zero4, 0, 0, 0);
;                 float o[4]; float ss = 0.f;
; #pragma unroll
;                 for (int r = 0; r < 4; ++r) { o[r] = (z0[r] + gb0[r]) * sigmoidf_(z1[r] + gb1[r]); ss += o[r] * o[r]; }
;                 u32x2 w; w.x = cvt_pk_bf16(o[0], o[1]); w.y = cvt_pk_bf16(o[2], o[3]);
;                 *(GAS u32x2*)(Y + (size_t)(pos0 + c) * DM + g * 16 + 4 * q) = w;
;                 ss += __shfl_xor(ss, 16); ss += __shfl_xor(ss, 32);
;                 if (q == 0) fx_add(rs2 + pos0 + c, ss, FX_RS);
	v_add_f32_e32 v196, 1.0, v196
	v_lshlrev_b32_e32 v120, 16, v124
	v_add_f32_e32 v197, 1.0, v197
	v_and_b32_e32 v121, 0xffff0000, v124
	v_pk_mov_b32 v[118:119], v[0:1], v[0:1] op_sel:[1,0]
	v_rcp_f32_e32 v204, v198
	v_lshlrev_b32_e32 v123, 16, v125
	v_add_f32_e32 v198, 1.0, v199
	v_cvt_pk_bf16_f32 v103, v118, v119
	v_pk_fma_f32 v[118:119], v[104:105], v[0:1], v[120:121]
	v_rcp_f32_e32 v196, v196
	v_and_b32_e32 v122, 0xffff0000, v125
	v_rcp_f32_e32 v197, v197
	v_pk_fma_f32 v[0:1], v[112:113], v[0:1], v[118:119] op_sel:[0,0,1] op_sel_hi:[1,1,0]
	v_add_u32_e32 v117, 0x1400, v160
	v_rcp_f32_e32 v205, v198
	v_pk_mov_b32 v[118:119], v[0:1], v[0:1] op_sel:[1,0]
	v_pk_mul_f32 v[196:197], v[192:193], v[196:197]
	ds_write2_b32 v117, v3, v103 offset0:80 offset1:148
	v_cvt_pk_bf16_f32 v3, v118, v119
	v_pk_mul_f32 v[192:193], v[194:195], v[204:205]
	v_pk_fma_f32 v[118:119], v[106:107], v[0:1], v[122:123] op_sel:[0,1,0] op_sel_hi:[1,0,1]
	v_cvt_pk_bf16_f32 v200, v196, v197
	s_waitcnt lgkmcnt(6)
	v_lshlrev_b32_e32 v125, 16, v126
	v_cvt_pk_bf16_f32 v201, v192, v193
	v_pk_fma_f32 v[0:1], v[112:113], v[0:1], v[118:119]
	v_and_b32_e32 v124, 0xffff0000, v126
	v_mfma_f32_16x16x32_bf16 v[176:179], v[64:67], v[200:203], 0
	v_pk_mov_b32 v[118:119], v[0:1], v[0:1] op_sel:[1,0]
	v_mfma_f32_16x16x32_bf16 v[180:183], v[60:63], v[200:203], 0
	v_lshlrev_b32_e32 v139, 16, v127
	v_cvt_pk_bf16_f32 v103, v118, v119
	v_pk_fma_f32 v[118:119], v[106:107], v[0:1], v[124:125] op_sel:[0,1,0] op_sel_hi:[1,0,1]
	v_and_b32_e32 v138, 0xffff0000, v127
	v_pk_fma_f32 v[0:1], v[112:113], v[0:1], v[118:119]
	v_add_u32_e32 v117, 0x1600, v160
	v_pk_mov_b32 v[118:119], v[0:1], v[0:1] op_sel:[1,0]
	ds_write2_b32 v117, v3, v103 offset0:88 offset1:156
	v_add_f32_e32 v176, v52, v176
	v_mul_f32_e32 v176, 0xbfb8aa3b, v176
	v_exp_f32_e32 v176, v176
	v_add_f32_e32 v177, v53, v177
	v_mul_f32_e32 v177, 0xbfb8aa3b, v177
	v_exp_f32_e32 v177, v177
	v_cvt_pk_bf16_f32 v3, v118, v119
	v_pk_fma_f32 v[118:119], v[106:107], v[0:1], v[138:139] op_sel:[0,1,0] op_sel_hi:[1,0,1]
	v_add_f32_e32 v198, v54, v178
	s_waitcnt lgkmcnt(6)
	v_add_f32_e32 v196, 1.0, v176
	v_lshlrev_b32_e32 v127, 16, v128
	v_pk_fma_f32 v[0:1], v[112:113], v[0:1], v[118:119]
	v_mul_f32_e32 v198, 0xbfb8aa3b, v198
	v_and_b32_e32 v126, 0xffff0000, v128
	v_add_f32_e32 v176, v55, v179
	v_pk_mov_b32 v[118:119], v[0:1], v[0:1] op_sel:[1,0]
	v_lshlrev_b32_e32 v141, 16, v129
	v_exp_f32_e32 v198, v198
	v_cvt_pk_bf16_f32 v103, v118, v119
	v_mul_f32_e32 v176, 0xbfb8aa3b, v176
	v_pk_fma_f32 v[118:119], v[106:107], v[0:1], v[126:127] op_sel:[0,1,0] op_sel_hi:[1,0,1]
	v_and_b32_e32 v140, 0xffff0000, v129
	v_exp_f32_e32 v179, v176
	v_pk_fma_f32 v[0:1], v[112:113], v[0:1], v[118:119]
	v_add_f32_e32 v197, 1.0, v177
	v_add_u32_e32 v117, 0x1800, v160
	v_rcp_f32_e32 v196, v196
	v_pk_mov_b32 v[118:119], v[0:1], v[0:1] op_sel:[1,0]
	ds_write2_b32 v117, v3, v103 offset0:96 offset1:164
	v_rcp_f32_e32 v197, v197
	v_cvt_pk_bf16_f32 v3, v118, v119
	v_add_f32_e32 v198, 1.0, v198
	v_pk_fma_f32 v[118:119], v[106:107], v[0:1], v[140:141] op_sel:[0,1,0] op_sel_hi:[1,0,1]
	s_waitcnt lgkmcnt(6)
	v_rcp_f32_e32 v178, v198
	v_lshlrev_b32_e32 v129, 16, v130
	v_add_f32_e32 v198, 1.0, v179
	v_pk_fma_f32 v[0:1], v[112:113], v[0:1], v[118:119]
	v_and_b32_e32 v128, 0xffff0000, v130
	v_pk_add_f32 v[176:177], v[56:57], v[180:181]
	v_pk_mov_b32 v[118:119], v[0:1], v[0:1] op_sel:[1,0]
	v_rcp_f32_e32 v179, v198
	v_lshlrev_b32_e32 v143, 16, v131
	v_cvt_pk_bf16_f32 v103, v118, v119
	v_pk_mul_f32 v[196:197], v[176:177], v[196:197]
	v_pk_fma_f32 v[118:119], v[106:107], v[0:1], v[128:129] op_sel:[0,1,0] op_sel_hi:[1,0,1]
	v_pk_add_f32 v[180:181], v[58:59], v[182:183]
	v_and_b32_e32 v142, 0xffff0000, v131
	v_pk_fma_f32 v[0:1], v[112:113], v[0:1], v[118:119]
	v_pk_mul_f32 v[176:177], v[196:197], v[196:197]
	v_add_u32_e32 v117, 0x1a00, v160
	v_pk_mul_f32 v[178:179], v[180:181], v[178:179]
	v_pk_mov_b32 v[118:119], v[0:1], v[0:1] op_sel:[1,0]
	ds_write2_b32 v117, v3, v103 offset0:104 offset1:172
	v_add_f32_e32 v198, v176, v177
	v_cvt_pk_bf16_f32 v3, v118, v119
	v_pk_mul_f32 v[180:181], v[178:179], v[178:179]
	v_pk_fma_f32 v[118:119], v[106:107], v[0:1], v[142:143] op_sel:[0,1,0] op_sel_hi:[1,0,1]
	v_add_f32_e32 v198, v180, v198
	s_waitcnt lgkmcnt(6)
	v_lshlrev_b32_e32 v131, 16, v136
	v_add_f32_e32 v198, v181, v198
	v_pk_fma_f32 v[0:1], v[112:113], v[0:1], v[118:119]
	v_cvt_pk_bf16_f32 v184, v196, v197
	v_and_b32_e32 v130, 0xffff0000, v136
	v_pk_mov_b32 v[118:119], v[0:1], v[0:1] op_sel:[1,0]
	v_cvt_pk_bf16_f32 v185, v178, v179
	v_lshlrev_b32_e32 v145, 16, v137
	v_mov_b32_e32 v189, v198
	v_cvt_pk_bf16_f32 v103, v118, v119
	v_pk_fma_f32 v[118:119], v[106:107], v[0:1], v[130:131] op_sel:[0,1,0] op_sel_hi:[1,0,1]
	s_nop 1
	v_and_b32_e32 v144, 0xffff0000, v137
	v_permlane16_swap_b32_e32 v198, v189
	v_pk_fma_f32 v[0:1], v[112:113], v[0:1], v[118:119]
	v_add_u32_e32 v117, 0x1c00, v160
	s_nop 1
	v_pk_mov_b32 v[118:119], v[0:1], v[0:1] op_sel:[1,0]
	v_add_f32_e32 v196, v198, v189
	ds_write2_b32 v117, v3, v103 offset0:112 offset1:180
	v_cvt_pk_bf16_f32 v3, v118, v119
	v_mov_b32_e32 v190, v196
	v_pk_fma_f32 v[118:119], v[106:107], v[0:1], v[144:145] op_sel:[0,1,0] op_sel_hi:[1,0,1]
	s_nop 1
	s_nop 0
	v_pk_fma_f32 v[118:119], v[112:113], v[0:1], v[118:119]
	v_permlane32_swap_b32_e32 v196, v190
	s_nop 0
	s_nop 1
	v_pk_mov_b32 v[0:1], v[118:119], v[118:119] op_sel:[1,0]
	v_add_f32_e32 v196, v196, v190
	s_nop 0
	v_cvt_pk_bf16_f32 v0, v0, v1
	v_add_u32_e32 v1, 0x1e00, v160
	ds_write2_b32 v1, v3, v0 offset0:120 offset1:188
	s_waitcnt lgkmcnt(0)
	v_add_u32_e32 v186, -16, v116
	v_ashrrev_i32_e32 v187, 31, v186
	v_lshlrev_b64 v[186:187], 12, v[186:187]
	v_lshl_add_u64 v[186:187], v[108:109], 0, v[186:187]
	s_cmp_eq_u32 s26, 0
	s_cbranch_scc1 .Lmy_s5_skip0
	global_store_dwordx2 v[186:187], v[184:185], off
	s_and_saveexec_b64 s[10:11], s[4:5]
	s_cbranch_execz .Lmy_s5_skip0
	v_mul_f32_e32 v196, 0x4b800000, v196
	v_rndne_f32_e32 v196, v196
	v_mul_f32_e64 v197, |v196|, s64
	v_floor_f32_e32 v197, v197
	v_fma_f32 v198, v197, s97, |v196|
	v_cvt_u32_f32_e32 v198, v198
	v_cvt_u32_f32_e32 v197, v197
	v_ashrrev_i32_e32 v188, 31, v196
	v_xor_b32_e32 v196, v198, v188
	v_xor_b32_e32 v197, v197, v188
	v_sub_co_u32_e32 v196, vcc, v196, v188
	s_nop 1
	v_subb_co_u32_e32 v197, vcc, v197, v188, vcc
	global_atomic_add_x2 v[114:115], v[196:197], off offset:-128
	s_branch .LBB0_333
